# attention map prologue: Q block loads issued before the bias-table load->wait section (prologue de-serialisation)
# baseline (speedup 1.0000x reference)
.LBB0_504:
	s_or_b32 s24, s13, s58
	s_ashr_i32 s25, s24, 31
	s_lshl_b64 s[44:45], s[24:25], 18
	v_mov_b32_e32 v2, v210
	v_mov_b32_e32 v4, v212
	v_mov_b32_e32 v6, v211
	s_add_u32 s24, s94, s44
	s_waitcnt lgkmcnt(0)
	s_barrier
	s_addc_u32 s25, s95, s45
	v_ashrrev_i32_e32 v3, 31, v2
	v_ashrrev_i32_e32 v7, 31, v6
	s_mov_b32 m0, s60
	v_lshl_add_u64 v[8:9], v[2:3], 1, s[24:25]
	v_lshlrev_b64 v[10:11], 1, v[6:7]
	global_load_lds_dwordx4 v[8:9], off
	v_lshl_add_u64 v[12:13], s[6:7], 0, v[10:11]
	s_add_i32 m0, s61, 0x2000
	v_ashrrev_i32_e32 v5, 31, v4
	global_load_lds_dwordx4 v[12:13], off
	v_lshlrev_b64 v[12:13], 1, v[4:5]
	v_lshl_add_u64 v[14:15], s[6:7], 0, v[12:13]
	s_add_i32 m0, s61, 0x2400
	v_lshl_add_u64 v[8:9], v[8:9], 0, s[90:91]
	global_load_lds_dwordx4 v[14:15], off
	s_add_i32 m0, s60, 0x6000
	s_and_b64 s[24:25], s[10:11], s[40:41]
	global_load_lds_dwordx4 v[8:9], off
	v_lshl_add_u64 v[8:9], s[8:9], 0, v[10:11]
	s_add_i32 m0, s61, 0x8000
	s_nop 0
	global_load_lds_dwordx4 v[8:9], off
	v_lshl_add_u64 v[8:9], s[8:9], 0, v[12:13]
	s_mov_b32 m0, s22
	s_nop 0
	global_load_lds_dwordx4 v[8:9], off
	v_lshl_add_u64 v[12:13], v[134:135], 0, s[44:45]
	v_lshl_add_u64 v[8:9], v[140:141], 1, v[12:13]
	global_load_dwordx4 v[66:69], v[8:9], off
	v_lshl_add_u64 v[8:9], v[142:143], 1, v[12:13]
	global_load_dwordx4 v[70:73], v[8:9], off
	v_lshl_add_u64 v[8:9], v[144:145], 1, v[12:13]
	global_load_dwordx4 v[74:77], v[8:9], off
	v_lshl_add_u64 v[8:9], v[146:147], 1, v[12:13]
	global_load_dwordx4 v[78:81], v[8:9], off
	s_and_saveexec_b64 s[48:49], s[24:25]
	s_cbranch_execz .LBB0_508
	v_mov_b32_e32 v0, 0xff800000
	s_and_saveexec_b64 s[50:51], s[42:43]
	s_cbranch_execz .LBB0_507
	global_load_dword v0, v[138:139], off
	s_waitcnt vmcnt(0)
	v_mul_f32_e32 v0, 0x3fb8aa3b, v0

.LBB0_508:
	s_or_b64 exec, exec, s[48:49]
	s_add_i32 s24, s58, s13
	s_ashr_i32 s25, s24, 31
	s_lshl_b64 s[24:25], s[24:25], 18
	v_mov_b32_e32 v14, v1
	v_mov_b32_e32 v15, v1
	v_lshl_add_u64 v[130:131], v[6:7], 1, s[4:5]
	v_lshl_add_u64 v[132:133], v[4:5], 1, s[4:5]
	v_lshl_add_u64 v[152:153], v[2:3], 1, s[24:25]
	v_mov_b32_e32 v0, v1
	v_mov_b32_e32 v2, v1
	v_mov_b32_e32 v3, v1
	v_mov_b32_e32 v4, v1
	v_mov_b32_e32 v5, v1
	v_mov_b32_e32 v6, v1
	v_mov_b32_e32 v7, v1
	s_xor_b64 s[10:11], s[10:11], -1
	s_mov_b32 s23, 0
	v_mov_b32_e32 v154, 0
	s_mov_b32 s24, 2
	s_mov_b32 s25, s20
	s_mov_b32 s26, 0
	v_mov_b32_e32 v155, 0
	s_mov_b32 s27, 0
	s_waitcnt vmcnt(0)
	ds_write_b128 v215, v[66:69]
	ds_write_b128 v216, v[70:73]
	ds_write_b128 v217, v[74:77]
	ds_write_b128 v218, v[78:81]
	v_mov_b32_e32 v12, v1
	v_mov_b32_e32 v13, v1
	v_mov_b32_e32 v8, v1
	v_mov_b32_e32 v9, v1
	v_mov_b32_e32 v10, v1
	v_mov_b32_e32 v11, v1
	v_mov_b64_e32 v[64:65], v[14:15]
	v_mov_b64_e32 v[48:49], v[14:15]
	v_mov_b64_e32 v[32:33], v[14:15]
	v_mov_b64_e32 v[62:63], v[12:13]
	v_mov_b64_e32 v[60:61], v[10:11]
	v_mov_b64_e32 v[58:59], v[8:9]
	v_mov_b64_e32 v[56:57], v[6:7]
	v_mov_b64_e32 v[54:55], v[4:5]
	v_mov_b64_e32 v[52:53], v[2:3]
	v_mov_b64_e32 v[50:51], v[0:1]
	v_mov_b64_e32 v[46:47], v[12:13]
	v_mov_b64_e32 v[44:45], v[10:11]
	v_mov_b64_e32 v[42:43], v[8:9]
	v_mov_b64_e32 v[40:41], v[6:7]
	v_mov_b64_e32 v[38:39], v[4:5]
	v_mov_b64_e32 v[36:37], v[2:3]
	v_mov_b64_e32 v[34:35], v[0:1]
	v_mov_b64_e32 v[30:31], v[12:13]
	v_mov_b64_e32 v[28:29], v[10:11]
	v_mov_b64_e32 v[26:27], v[8:9]
	v_mov_b64_e32 v[24:25], v[6:7]
	v_mov_b64_e32 v[22:23], v[4:5]
	v_mov_b64_e32 v[20:21], v[2:3]
	v_mov_b64_e32 v[18:19], v[0:1]
	v_mov_b64_e32 v[16:17], v[14:15]
	v_mov_b64_e32 v[14:15], v[12:13]
	v_mov_b64_e32 v[12:13], v[10:11]
	v_mov_b64_e32 v[10:11], v[8:9]
	v_mov_b64_e32 v[8:9], v[6:7]
	v_mov_b64_e32 v[6:7], v[4:5]
	v_mov_b64_e32 v[4:5], v[2:3]
	v_mov_b64_e32 v[2:3], v[0:1]
	s_branch .LBB0_511
